# out-proj GEMM epilogue: first-half X stores drained before the second-half X loads are issued
# speedup vs baseline: 1.0077x; 1.0000x over previous
;     __device__ __forceinline__ void operator()(const f32x4 (&acc)[2][2][4][2], const Unit& u, int wr, int wc, int fr, int fq) const {
;     ...
;         for (int ai = 0; ai < 2; ++ai) {
;             f32x4 xo[4][2][2];
; #pragma unroll
;             for (int m = 0; m < 4; ++m) { const int row = row0 + ai * HALF + m * 16;
;                 const float* srcp = (vs < 2 ? Rlat + (size_t)row * DM : Rctx + (size_t)(row - TL) * DM) + col0;
; #pragma unroll
;                 for (int bj = 0; bj < 2; ++bj)
; #pragma unroll
;                     for (int n = 0; n < 2; ++n) xo[m][bj][n] = *(const f32x4*)(srcp + bj * HALF + n * 16); }
; #pragma unroll
;             for (int m = 0; m < 4; ++m) { const int row = row0 + ai * HALF + m * 16; float* rowp = X + (size_t)row * DM + col0;
; #pragma unroll
;                 for (int bj = 0; bj < 2; ++bj)
; #pragma unroll
;                     for (int n = 0; n < 2; ++n) *(f32x4*)(rowp + bj * HALF + n * 16) = xo[m][bj][n] + gv[bj][n] * acc[ai][bj][m][n]; } }
.LBB0_2573:
	v_lshl_add_u64 v[146:147], v[148:149], 0, v[222:223]
	global_load_dwordx4 v[158:161], v[146:147], off
	global_load_dwordx4 v[154:157], v[146:147], off offset:64
	global_load_dwordx4 v[150:153], v[146:147], off offset:512
	s_nop 0
	global_load_dwordx4 v[146:149], v[146:147], off offset:576
	v_lshlrev_b64 v[228:229], 13, v[224:225]
	s_waitcnt vmcnt(0)
	v_pk_fma_f32 v[208:209], v[128:129], v[144:145], v[208:209]
	v_pk_fma_f32 v[206:207], v[126:127], v[142:143], v[206:207]
	v_ashrrev_i32_e32 v227, 31, v226
	v_add_u32_e32 v128, 0x80, v224
	v_add_u32_e32 v127, 0xffffc080, v224
	v_ashrrev_i32_e32 v231, 31, v230
	v_pk_fma_f32 v[90:91], v[90:91], v[138:139], v[170:171]
	v_pk_fma_f32 v[86:87], v[86:87], v[134:135], v[166:167]
	v_pk_fma_f32 v[84:85], v[84:85], v[132:133], v[164:165]
	v_add_u32_e32 v126, 0x90, v224
	v_add_u32_e32 v129, 0xffffc090, v224
	v_lshl_add_u64 v[164:165], s[0:1], 0, v[228:229]
	v_lshlrev_b64 v[166:167], 13, v[226:227]
	v_cndmask_b32_e64 v170, v127, v128, s[4:5]
	v_pk_fma_f32 v[118:119], v[118:119], v[134:135], v[198:199]
	v_pk_fma_f32 v[110:111], v[110:111], v[130:131], v[194:195]
	v_pk_fma_f32 v[92:93], v[92:93], v[140:141], v[172:173]
	v_pk_fma_f32 v[88:89], v[88:89], v[136:137], v[168:169]
	v_pk_fma_f32 v[82:83], v[82:83], v[130:131], v[162:163]
	v_lshl_add_u64 v[162:163], s[0:1], 0, v[232:233]
	v_lshlrev_b64 v[168:169], 13, v[230:231]
	v_cndmask_b32_e64 v172, v129, v126, s[4:5]
	v_lshl_add_u64 v[164:165], v[164:165], 0, v[222:223]
	v_lshl_add_u64 v[166:167], s[0:1], 0, v[166:167]
	v_ashrrev_i32_e32 v171, 31, v170
	v_pk_fma_f32 v[124:125], v[124:125], v[140:141], v[204:205]
	v_pk_fma_f32 v[122:123], v[122:123], v[138:139], v[202:203]
	v_pk_fma_f32 v[120:121], v[120:121], v[136:137], v[200:201]
	v_pk_fma_f32 v[112:113], v[112:113], v[132:133], v[196:197]
	v_pk_fma_f32 v[116:117], v[116:117], v[144:145], v[192:193]
	v_pk_fma_f32 v[114:115], v[114:115], v[142:143], v[190:191]
	v_lshl_add_u64 v[162:163], v[162:163], 0, v[222:223]
	v_lshl_add_u64 v[168:169], s[0:1], 0, v[168:169]
	v_ashrrev_i32_e32 v173, 31, v172
	global_store_dwordx4 v[164:165], v[206:209], off
	global_store_dwordx4 v[164:165], v[122:125], off offset:64
	global_store_dwordx4 v[164:165], v[118:121], off offset:512
	global_store_dwordx4 v[164:165], v[110:113], off offset:576
	v_pk_fma_f32 v[108:109], v[108:109], v[140:141], v[188:189]
	v_lshlrev_b64 v[118:119], 13, v[170:171]
	v_lshl_add_u64 v[110:111], v[166:167], 0, v[222:223]
	v_pk_fma_f32 v[106:107], v[106:107], v[138:139], v[186:187]
	v_pk_fma_f32 v[104:105], v[104:105], v[136:137], v[184:185]
	v_pk_fma_f32 v[102:103], v[102:103], v[134:135], v[182:183]
	v_pk_fma_f32 v[96:97], v[96:97], v[132:133], v[180:181]
	v_pk_fma_f32 v[94:95], v[94:95], v[130:131], v[178:179]
	v_pk_fma_f32 v[100:101], v[100:101], v[144:145], v[176:177]
	v_pk_fma_f32 v[98:99], v[98:99], v[142:143], v[174:175]
	v_lshl_add_u64 v[112:113], v[168:169], 0, v[222:223]
	v_lshlrev_b64 v[120:121], 13, v[172:173]
	global_store_dwordx4 v[110:111], v[114:117], off
	global_store_dwordx4 v[110:111], v[106:109], off offset:64
	global_store_dwordx4 v[110:111], v[102:105], off offset:512
	global_store_dwordx4 v[110:111], v[94:97], off offset:576
	global_store_dwordx4 v[112:113], v[98:101], off
	global_store_dwordx4 v[112:113], v[90:93], off offset:64
	global_store_dwordx4 v[112:113], v[86:89], off offset:512
	global_store_dwordx4 v[112:113], v[82:85], off offset:576
	v_add_u32_e32 v124, 0xa0, v224
	s_andn2_b64 vcc, exec, s[14:15]
	v_lshl_add_u64 v[82:83], s[22:23], 0, v[118:119]
	v_lshl_add_u64 v[84:85], s[22:23], 0, v[120:121]
	v_lshl_add_u64 v[82:83], v[82:83], 0, v[222:223]
	v_lshl_add_u64 v[84:85], v[84:85], 0, v[222:223]
	s_mov_b64 s[54:55], 0x60000
	v_pk_fma_f32 v[80:81], v[80:81], v[144:145], v[160:161]
	v_pk_fma_f32 v[78:79], v[78:79], v[142:143], v[158:159]
	v_pk_fma_f32 v[76:77], v[76:77], v[140:141], v[156:157]
	v_pk_fma_f32 v[66:67], v[66:67], v[130:131], v[146:147]
	v_pk_fma_f32 v[74:75], v[74:75], v[138:139], v[154:155]
	v_pk_fma_f32 v[72:73], v[72:73], v[136:137], v[152:153]
	v_pk_fma_f32 v[70:71], v[70:71], v[134:135], v[150:151]
	v_pk_fma_f32 v[68:69], v[68:69], v[132:133], v[148:149]
	global_store_dwordx4 v[162:163], v[78:81], off
	global_store_dwordx4 v[162:163], v[74:77], off offset:64
	global_store_dwordx4 v[162:163], v[70:73], off offset:512
	global_store_dwordx4 v[162:163], v[66:69], off offset:576
	s_waitcnt vmcnt(0)
	global_load_dwordx4 v[118:121], v[82:83], off
	global_load_dwordx4 v[114:117], v[82:83], off offset:64
	global_load_dwordx4 v[110:113], v[82:83], off offset:512
	global_load_dwordx4 v[106:109], v[82:83], off offset:576
	global_load_dwordx4 v[102:105], v[84:85], off
	global_load_dwordx4 v[98:101], v[84:85], off offset:64
	global_load_dwordx4 v[94:97], v[84:85], off offset:512
	global_load_dwordx4 v[90:93], v[84:85], off offset:576
	v_add_u32_e32 v66, 0xffffc0a0, v224
	v_cndmask_b32_e64 v66, v66, v124, s[4:5]
	v_ashrrev_i32_e32 v67, 31, v66
	v_lshlrev_b64 v[66:67], 13, v[66:67]
	v_lshl_add_u64 v[66:67], s[22:23], 0, v[66:67]
	v_lshl_add_u64 v[66:67], v[66:67], 0, v[222:223]
	global_load_dwordx4 v[86:89], v[66:67], off
	global_load_dwordx4 v[78:81], v[66:67], off offset:64
	global_load_dwordx4 v[70:73], v[66:67], off offset:512
	s_nop 0
	global_load_dwordx4 v[66:69], v[66:67], off offset:576
	v_add_u32_e32 v74, 0xb0, v224
	s_mov_b64 s[4:5], -1
	v_ashrrev_i32_e32 v75, 31, v74
	s_cbranch_vccnz .LBB0_2575
	s_mov_b32 s4, 0xf8160000
	v_lshl_add_u64 v[76:77], s[10:11], 0, v[228:229]
	s_mov_b32 s5, -1
	v_lshl_add_u64 v[76:77], v[76:77], 0, s[4:5]
	v_lshlrev_b64 v[122:123], 13, v[74:75]
	s_mov_b64 s[4:5], 0
